# p=3 sample_in_gemm: both K-slices requested before the barrier (second slice in spare VGPRs), on top of v8
# speedup vs baseline: 1.0038x; 1.0038x over previous
.LBB0_641:
	s_ashr_i32 s2, s8, 31
	s_lshr_b32 s2, s2, 29
	s_add_i32 s2, s8, s2
	s_ashr_i32 s2, s2, 3
	s_lshl_b32 s15, s2, 9
	s_add_i32 s14, s2, s11
	s_sub_i32 s2, s12, s15
	v_add_u32_e32 v20, s2, v4
	v_ashrrev_i32_e32 v21, 31, v20
	v_lshlrev_b64 v[20:21], 11, v[20:21]
	v_lshl_add_u64 v[76:77], v[0:1], 0, v[20:21]
	v_add_co_u32_e64 v78, s[2:3], s50, v76
	s_mov_b32 s17, 0x8000
	s_nop 0
	v_addc_co_u32_e64 v79, s[2:3], 0, v77, s[2:3]
	v_add_co_u32_e64 v80, s[2:3], s17, v76
	s_mov_b32 s18, 0xc000
	s_nop 0
	v_addc_co_u32_e64 v81, s[2:3], 0, v77, s[2:3]
	v_add_co_u32_e64 v82, s[2:3], s18, v76
	s_mov_b32 s16, 0x14000
	s_nop 0
	v_addc_co_u32_e64 v83, s[2:3], 0, v77, s[2:3]
	v_add_co_u32_e64 v84, s[2:3], s58, v76
	s_mul_i32 s14, s14, 48
	s_nop 0
	v_addc_co_u32_e64 v85, s[2:3], 0, v77, s[2:3]
	v_add_co_u32_e64 v86, s[2:3], s16, v76
	v_or_b32_e32 v22, s14, v4
	s_nop 0
	v_addc_co_u32_e64 v87, s[2:3], 0, v77, s[2:3]
	s_mov_b32 s2, 0x18000
	s_nop 0
	v_add_co_u32_e64 v88, s[2:3], s2, v76
	v_ashrrev_i32_e32 v23, 31, v22
	s_nop 0
	v_addc_co_u32_e64 v89, s[2:3], 0, v77, s[2:3]
	s_mov_b32 s2, 0x1c000
	v_lshlrev_b64 v[52:53], 11, v[22:23]
	v_add_co_u32_e64 v90, s[2:3], s2, v76
	v_lshl_add_u64 v[92:93], v[2:3], 0, v[52:53]
	s_nop 0
	v_addc_co_u32_e64 v91, s[2:3], 0, v77, s[2:3]
	v_add_co_u32_e64 v94, s[2:3], s50, v92
	global_load_dwordx4 v[20:23], v[76:77], off
	global_load_dwordx4 v[24:27], v[78:79], off
	v_addc_co_u32_e64 v95, s[2:3], 0, v93, s[2:3]
	v_add_co_u32_e64 v96, s[2:3], s17, v92
	global_load_dwordx4 v[28:31], v[80:81], off
	global_load_dwordx4 v[32:35], v[82:83], off
	v_addc_co_u32_e64 v97, s[2:3], 0, v93, s[2:3]
	v_add_co_u32_e64 v98, s[2:3], s18, v92
	global_load_dwordx4 v[36:39], v[84:85], off
	global_load_dwordx4 v[40:43], v[86:87], off
	v_addc_co_u32_e64 v99, s[2:3], 0, v93, s[2:3]
	v_add_co_u32_e64 v100, s[2:3], s58, v92
	global_load_dwordx4 v[44:47], v[88:89], off
	global_load_dwordx4 v[48:51], v[90:91], off
	v_addc_co_u32_e64 v101, s[2:3], 0, v93, s[2:3]
	v_add_co_u32_e64 v102, s[2:3], s16, v92
	global_load_dwordx4 v[52:55], v[92:93], off
	global_load_dwordx4 v[56:59], v[94:95], off
	global_load_dwordx4 v[60:63], v[96:97], off
	global_load_dwordx4 v[64:67], v[98:99], off
	v_addc_co_u32_e64 v103, s[2:3], 0, v93, s[2:3]
	global_load_dwordx4 v[68:71], v[100:101], off
	global_load_dwordx4 v[72:75], v[102:103], off
	global_load_dwordx4 v[148:151], v[102:103], off offset:128
	global_load_dwordx4 v[152:155], v[100:101], off offset:128
	global_load_dwordx4 v[156:159], v[98:99], off offset:128
	global_load_dwordx4 v[160:163], v[96:97], off offset:128
	global_load_dwordx4 v[164:167], v[94:95], off offset:128
	global_load_dwordx4 v[168:171], v[92:93], off offset:128
	global_load_dwordx4 v[172:175], v[90:91], off offset:128
	global_load_dwordx4 v[176:179], v[88:89], off offset:128
	global_load_dwordx4 v[180:183], v[86:87], off offset:128
	global_load_dwordx4 v[184:187], v[84:85], off offset:128
	global_load_dwordx4 v[188:191], v[82:83], off offset:128
	global_load_dwordx4 v[192:195], v[80:81], off offset:128
	global_load_dwordx4 v[196:199], v[78:79], off offset:128
	global_load_dwordx4 v[200:203], v[76:77], off offset:128
	s_barrier
	s_waitcnt vmcnt(27)
	ds_write_b128 v16, v[20:23]
	s_waitcnt vmcnt(26)
	ds_write_b128 v16, v[24:27] offset:1024
	s_waitcnt vmcnt(25)
	ds_write_b128 v16, v[28:31] offset:2048
	s_waitcnt vmcnt(24)
	ds_write_b128 v16, v[32:35] offset:3072
	s_waitcnt vmcnt(23)
	ds_write_b128 v16, v[36:39] offset:4096
	s_waitcnt vmcnt(22)
	ds_write_b128 v16, v[40:43] offset:5120
	s_waitcnt vmcnt(21)
	ds_write_b128 v16, v[44:47] offset:6144
	s_waitcnt vmcnt(20)
	ds_write_b128 v16, v[48:51] offset:7168
	s_waitcnt vmcnt(19)
	ds_write_b128 v16, v[52:55] offset:8192
	s_waitcnt vmcnt(18)
	ds_write_b128 v16, v[56:59] offset:9216
	s_waitcnt vmcnt(17)
	ds_write_b128 v16, v[60:63] offset:10240
	s_waitcnt vmcnt(16)
	ds_write_b128 v16, v[64:67] offset:11264
	s_waitcnt vmcnt(15)
	ds_write_b128 v16, v[68:71] offset:12288
	s_waitcnt vmcnt(14)
	ds_write_b128 v16, v[72:75] offset:13312
	ds_read_b128 v[76:79], v17 offset:8192
	ds_read_b128 v[80:83], v17
	ds_read_b128 v[88:91], v17 offset:10240
	ds_read_b128 v[124:127], v17 offset:6144
	ds_read_b128 v[96:99], v17 offset:12288
	ds_read_b128 v[128:131], v18 offset:8192
	ds_read_b128 v[100:103], v17 offset:2048
	ds_read_b128 v[112:115], v17 offset:4096
	s_waitcnt lgkmcnt(6)
	v_mfma_f32_16x16x32_bf16 v[84:87], v[76:79], v[80:83], 0
	ds_read_b128 v[136:139], v18 offset:12288
	ds_read_b128 v[132:135], v18 offset:10240
	s_waitcnt lgkmcnt(7)
	v_mfma_f32_16x16x32_bf16 v[92:95], v[88:91], v[80:83], 0
	s_waitcnt lgkmcnt(5)
	v_mfma_f32_16x16x32_bf16 v[80:83], v[96:99], v[80:83], 0
	s_waitcnt lgkmcnt(3)
	v_mfma_f32_16x16x32_bf16 v[104:107], v[76:79], v[100:103], 0
	v_mfma_f32_16x16x32_bf16 v[108:111], v[88:91], v[100:103], 0
	v_mfma_f32_16x16x32_bf16 v[100:103], v[96:99], v[100:103], 0
	s_waitcnt lgkmcnt(2)
	v_mfma_f32_16x16x32_bf16 v[116:119], v[76:79], v[112:115], 0
	v_mfma_f32_16x16x32_bf16 v[120:123], v[88:91], v[112:115], 0
	v_mfma_f32_16x16x32_bf16 v[112:115], v[96:99], v[112:115], 0
	v_mfma_f32_16x16x32_bf16 v[76:79], v[76:79], v[124:127], 0
	v_mfma_f32_16x16x32_bf16 v[88:91], v[88:91], v[124:127], 0
	v_mfma_f32_16x16x32_bf16 v[96:99], v[96:99], v[124:127], 0
	ds_read_b128 v[124:127], v18
	s_waitcnt lgkmcnt(0)
	v_mfma_f32_16x16x32_bf16 v[84:87], v[128:131], v[124:127], v[84:87]
	v_mfma_f32_16x16x32_bf16 v[92:95], v[132:135], v[124:127], v[92:95]
	v_mfma_f32_16x16x32_bf16 v[80:83], v[136:139], v[124:127], v[80:83]
	ds_read_b128 v[124:127], v18 offset:2048
	s_waitcnt lgkmcnt(0)
	v_mfma_f32_16x16x32_bf16 v[104:107], v[128:131], v[124:127], v[104:107]
	v_mfma_f32_16x16x32_bf16 v[108:111], v[132:135], v[124:127], v[108:111]
	v_mfma_f32_16x16x32_bf16 v[100:103], v[136:139], v[124:127], v[100:103]
	ds_read_b128 v[124:127], v18 offset:4096
	s_waitcnt lgkmcnt(0)
	v_mfma_f32_16x16x32_bf16 v[116:119], v[128:131], v[124:127], v[116:119]
	v_mfma_f32_16x16x32_bf16 v[120:123], v[132:135], v[124:127], v[120:123]
	v_mfma_f32_16x16x32_bf16 v[112:115], v[136:139], v[124:127], v[112:115]
	ds_read_b128 v[124:127], v18 offset:6144
	s_waitcnt lgkmcnt(0)
	v_mfma_f32_16x16x32_bf16 v[76:79], v[128:131], v[124:127], v[76:79]
	v_mfma_f32_16x16x32_bf16 v[88:91], v[132:135], v[124:127], v[88:91]
	v_mfma_f32_16x16x32_bf16 v[96:99], v[136:139], v[124:127], v[96:99]
	s_waitcnt vmcnt(0)
	ds_write_b128 v16, v[200:203]
	ds_write_b128 v16, v[196:199] offset:1024
	ds_write_b128 v16, v[192:195] offset:2048
	ds_write_b128 v16, v[188:191] offset:3072
	ds_write_b128 v16, v[184:187] offset:4096
	ds_write_b128 v16, v[180:183] offset:5120
	ds_write_b128 v16, v[176:179] offset:6144
	ds_write_b128 v16, v[172:175] offset:7168
	ds_write_b128 v16, v[168:171] offset:8192
	ds_write_b128 v16, v[164:167] offset:9216
	ds_write_b128 v16, v[160:163] offset:10240
	ds_write_b128 v16, v[156:159] offset:11264
	ds_write_b128 v16, v[152:155] offset:12288
	ds_write_b128 v16, v[148:151] offset:13312
	ds_read_b128 v[20:23], v17 offset:8192
	ds_read_b128 v[24:27], v17
	ds_read_b128 v[32:35], v17 offset:10240
	ds_read_b128 v[68:71], v17 offset:6144
	ds_read_b128 v[40:43], v17 offset:12288
	ds_read_b128 v[72:75], v18 offset:8192
	ds_read_b128 v[44:47], v17 offset:2048
	ds_read_b128 v[56:59], v17 offset:4096
	s_waitcnt lgkmcnt(6)
	v_mfma_f32_16x16x32_bf16 v[28:31], v[20:23], v[24:27], v[84:87]
	s_waitcnt lgkmcnt(5)
	v_mfma_f32_16x16x32_bf16 v[36:39], v[32:35], v[24:27], v[92:95]
	s_waitcnt lgkmcnt(3)
	v_mfma_f32_16x16x32_bf16 v[24:27], v[40:43], v[24:27], v[80:83]
	s_waitcnt lgkmcnt(1)
	v_mfma_f32_16x16x32_bf16 v[48:51], v[20:23], v[44:47], v[104:107]
	s_nop 0
	ds_read_b128 v[80:83], v18 offset:12288
	v_mfma_f32_16x16x32_bf16 v[52:55], v[32:35], v[44:47], v[108:111]
	v_mfma_f32_16x16x32_bf16 v[44:47], v[40:43], v[44:47], v[100:103]
	s_waitcnt lgkmcnt(1)
	v_mfma_f32_16x16x32_bf16 v[60:63], v[20:23], v[56:59], v[116:119]
	v_mfma_f32_16x16x32_bf16 v[64:67], v[32:35], v[56:59], v[120:123]
	v_mfma_f32_16x16x32_bf16 v[56:59], v[40:43], v[56:59], v[112:115]
	v_mfma_f32_16x16x32_bf16 v[20:23], v[20:23], v[68:71], v[76:79]
	v_mfma_f32_16x16x32_bf16 v[32:35], v[32:35], v[68:71], v[88:91]
	s_nop 1
	ds_read_b128 v[76:79], v18 offset:10240
	v_mfma_f32_16x16x32_bf16 v[40:43], v[40:43], v[68:71], v[96:99]
	ds_read_b128 v[68:71], v18
	s_waitcnt lgkmcnt(0)
	v_mfma_f32_16x16x32_bf16 v[28:31], v[72:75], v[68:71], v[28:31]
	v_mfma_f32_16x16x32_bf16 v[36:39], v[76:79], v[68:71], v[36:39]
	v_mfma_f32_16x16x32_bf16 v[24:27], v[80:83], v[68:71], v[24:27]
	ds_read_b128 v[68:71], v18 offset:2048
	s_waitcnt lgkmcnt(0)
	v_mfma_f32_16x16x32_bf16 v[48:51], v[72:75], v[68:71], v[48:51]
	v_mfma_f32_16x16x32_bf16 v[52:55], v[76:79], v[68:71], v[52:55]
	v_mfma_f32_16x16x32_bf16 v[44:47], v[80:83], v[68:71], v[44:47]
	ds_read_b128 v[68:71], v18 offset:4096
	s_waitcnt lgkmcnt(0)
	v_mfma_f32_16x16x32_bf16 v[60:63], v[72:75], v[68:71], v[60:63]
	v_mfma_f32_16x16x32_bf16 v[64:67], v[76:79], v[68:71], v[64:67]
	v_mfma_f32_16x16x32_bf16 v[56:59], v[80:83], v[68:71], v[56:59]
	ds_read_b128 v[68:71], v18 offset:6144
	s_waitcnt lgkmcnt(0)
	v_mfma_f32_16x16x32_bf16 v[20:23], v[72:75], v[68:71], v[20:23]
	v_mfma_f32_16x16x32_bf16 v[32:35], v[76:79], v[68:71], v[32:35]
	v_mfma_f32_16x16x32_bf16 v[40:43], v[80:83], v[68:71], v[40:43]
	s_barrier
	ds_write_b128 v5, v[28:31]
	ds_write_b128 v5, v[36:39] offset:1024
	ds_write_b128 v5, v[24:27] offset:2048
	ds_write_b128 v5, v[48:51] offset:3072
	ds_write_b128 v5, v[52:55] offset:4096
	ds_write_b128 v5, v[44:47] offset:5120
	ds_write_b128 v5, v[60:63] offset:6144
	ds_write_b128 v5, v[64:67] offset:7168
	ds_write_b128 v5, v[56:59] offset:8192
	ds_write_b128 v5, v[20:23] offset:9216
	ds_write_b128 v5, v[32:35] offset:10240
	ds_write_b128 v5, v[40:43] offset:11264
	s_waitcnt lgkmcnt(0)
	s_barrier
	s_and_saveexec_b64 s[2:3], vcc
	s_cbranch_execz .LBB0_640
	ds_read_b128 v[20:23], v6
	ds_read_b128 v[24:27], v6 offset:12288
	s_sub_i32 s15, 0, s15
	s_add_i32 s15, s15, s12
	v_add_u32_e32 v19, s15, v15
	s_waitcnt lgkmcnt(0)
	v_pk_add_f32 v[26:27], v[22:23], v[26:27]
	v_pk_add_f32 v[24:25], v[20:21], v[24:25]
	ds_read_b128 v[20:23], v6 offset:24576
	s_waitcnt lgkmcnt(0)
	v_pk_add_f32 v[26:27], v[26:27], v[22:23]
	v_pk_add_f32 v[24:25], v[24:25], v[20:21]
	ds_read_b128 v[20:23], v6 offset:36864
	s_waitcnt lgkmcnt(0)
	v_pk_add_f32 v[26:27], v[26:27], v[22:23]
	v_pk_add_f32 v[24:25], v[24:25], v[20:21]
	ds_read_b128 v[20:23], v6 offset:49152
	s_waitcnt lgkmcnt(0)
	v_pk_add_f32 v[26:27], v[26:27], v[22:23]
	v_pk_add_f32 v[24:25], v[24:25], v[20:21]
	ds_read_b128 v[20:23], v6 offset:61440
	s_waitcnt lgkmcnt(0)
	v_pk_add_f32 v[26:27], v[26:27], v[22:23]
	v_pk_add_f32 v[24:25], v[24:25], v[20:21]
	ds_read_b128 v[20:23], v7
	s_waitcnt lgkmcnt(0)
	v_pk_add_f32 v[26:27], v[26:27], v[22:23]
	v_pk_add_f32 v[24:25], v[24:25], v[20:21]
	ds_read_b128 v[20:23], v8
	s_waitcnt lgkmcnt(0)
	v_pk_add_f32 v[22:23], v[26:27], v[22:23]
	v_pk_add_f32 v[20:21], v[24:25], v[20:21]
	v_add_u32_e32 v24, s14, v9
	v_cvt_pk_bf16_f32 v20, v20, v21
	v_cvt_pk_bf16_f32 v21, v22, v23
	v_mov_b64_e32 v[22:23], s[4:5]
	v_ashrrev_i32_e32 v25, 31, v24
	v_mad_i64_i32 v[22:23], s[16:17], v19, s89, v[22:23]
	v_lshl_add_u64 v[22:23], v[24:25], 1, v[22:23]
	global_store_dwordx2 v[22:23], v[20:21], off
	s_and_b64 exec, exec, s[0:1]
	s_cbranch_execz .LBB0_640
	ds_read_b128 v[20:23], v6 offset:8192
	ds_read_b128 v[24:27], v6 offset:20480
	v_add_u32_e32 v19, s15, v14
	s_waitcnt lgkmcnt(0)
	v_pk_add_f32 v[26:27], v[22:23], v[26:27]
	v_pk_add_f32 v[24:25], v[20:21], v[24:25]
	ds_read_b128 v[20:23], v6 offset:32768
	s_waitcnt lgkmcnt(0)
	v_pk_add_f32 v[26:27], v[26:27], v[22:23]
	v_pk_add_f32 v[24:25], v[24:25], v[20:21]
	ds_read_b128 v[20:23], v6 offset:45056
	s_waitcnt lgkmcnt(0)
	v_pk_add_f32 v[26:27], v[26:27], v[22:23]
	v_pk_add_f32 v[24:25], v[24:25], v[20:21]
	ds_read_b128 v[20:23], v6 offset:57344
	s_waitcnt lgkmcnt(0)
	v_pk_add_f32 v[26:27], v[26:27], v[22:23]
	v_pk_add_f32 v[24:25], v[24:25], v[20:21]
	ds_read_b128 v[20:23], v10 offset:61440
	s_waitcnt lgkmcnt(0)
	v_pk_add_f32 v[26:27], v[26:27], v[22:23]
	v_pk_add_f32 v[24:25], v[24:25], v[20:21]
	ds_read_b128 v[20:23], v11
	s_waitcnt lgkmcnt(0)
	v_pk_add_f32 v[26:27], v[26:27], v[22:23]
	v_pk_add_f32 v[24:25], v[24:25], v[20:21]
	ds_read_b128 v[20:23], v12
	s_waitcnt lgkmcnt(0)
	v_pk_add_f32 v[22:23], v[26:27], v[22:23]
	v_pk_add_f32 v[20:21], v[24:25], v[20:21]
	v_add_u32_e32 v24, s14, v13
	v_cvt_pk_bf16_f32 v20, v20, v21
	v_cvt_pk_bf16_f32 v21, v22, v23
	v_mov_b64_e32 v[22:23], s[4:5]
	v_ashrrev_i32_e32 v25, 31, v24
	v_mad_i64_i32 v[22:23], s[14:15], v19, s89, v[22:23]
	v_lshl_add_u64 v[22:23], v[24:25], 1, v[22:23]
	global_store_dwordx2 v[22:23], v[20:21], off
	s_branch .LBB0_640
